# phase-3 transpose hook moved to the 160 workgroups with the lightest NSA items (bid<160) instead of bid 256..415
# speedup vs baseline: 1.0031x; 1.0031x over previous
.LBB0_230:
	v_readlane_b32 s64, v209, 33
	v_readlane_b32 s62, v209, 35
	s_mov_b64 s[40:41], 0
	v_readlane_b32 s60, v209, 37
	v_readlane_b32 s65, v209, 34
	v_readlane_b32 s63, v209, 36
	v_readlane_b32 s61, v209, 38
	s_cmpk_eq_i32 s72, 0x200
	s_cbranch_scc0 .Lp3h_no
	s_mov_b32 s50, s60
	s_cmpk_lt_u32 s50, 0xa0
	s_cbranch_scc0 .Lp3h_no
	s_add_i32 s50, s50, 0x168
	s_movk_i32 s51, 0x200
	s_movk_i32 s52, 0x207
	s_movk_i32 s53, 0x440
	s_movk_i32 s54, 0x1e8
	s_add_u32 s46, s12, 8
	s_addc_u32 s47, s13, 0
	s_branch .Ltramp_p0a
